# k20: k18 + attention queue ticket atomic no longer waited for right after issue (returns into the ticket register, consumed at the next unit)
# baseline (speedup 1.0000x reference)
; #define CTL WSP(unsigned, WS_CTL)
; __global__ void __launch_bounds__(NTHR, 2) hymba_fwd(Params P) {
;     ...
;         for (;;) {
;             asm volatile("s_waitcnt lgkmcnt(0)\n\ts_barrier" ::: "memory");
;             if (tid == 0) { uw[0] = nxt_ui; nxt_ui = atomicAdd(CTL + 64 + 64 * rep, 1u); }
;             asm volatile("s_waitcnt lgkmcnt(0)\n\ts_barrier" ::: "memory");
;             const int ui = __builtin_amdgcn_readfirstlane((int)uw[0]);
;             if (ui >= NUNITS) break;
.LBB0_721:
	s_waitcnt lgkmcnt(0)
	s_barrier
	s_and_saveexec_b64 s[6:7], s[4:5]
	s_cbranch_execz .LBB0_725
	s_mov_b64 s[8:9], exec
	v_mov_b32_e32 v0, s21
	ds_write_b32 v0, v129
	v_mbcnt_lo_u32_b32 v0, s8, 0
	v_mbcnt_hi_u32_b32 v0, s9, v0
	v_cmp_eq_u32_e32 vcc, 0, v0
	s_and_saveexec_b64 s[10:11], vcc
	s_cbranch_execz .LBB0_724
	s_bcnt1_i32_b64 s8, s[8:9]
	v_mov_b32_e32 v2, s8
	global_atomic_add v129, v1, v2, s[92:93] offset:256 sc0
.LBB0_724:
	s_or_b64 exec, exec, s[10:11]
.LBB0_725:
	s_or_b64 exec, exec, s[6:7]
	s_waitcnt lgkmcnt(0)
	s_barrier
	ds_read_b32 v0, v133
	s_mov_b64 s[6:7], -1
	s_waitcnt lgkmcnt(0)
	v_readfirstlane_b32 s52, v0
	s_cmpk_gt_i32 s52, 0x83f
	s_cbranch_scc1 .LBB0_720
	s_cmp_gt_i32 s52, 63
	s_cselect_b64 s[62:63], -1, 0
	s_mov_b64 s[48:49], -1
	s_and_b64 vcc, exec, s[62:63]
	s_cbranch_vccnz .LBB0_728
	s_ashr_i32 s12, s52, 3
	s_lshl_b32 s6, s12, 6
	s_add_i32 s34, s6, 0x10000
	s_ashr_i32 s35, s34, 31
	s_and_b32 s53, s52, 7
	s_lshl_b64 s[44:45], s[34:35], 9
	s_lshl_b64 s[6:7], s[34:35], 10
	s_add_u32 s6, s26, s6
	s_addc_u32 s7, s27, s7
	s_lshl_b32 s28, s53, 6
	s_lshl_b32 s8, s53, 7
	s_add_u32 s6, s6, s8
	s_addc_u32 s7, s7, 0
	s_mul_i32 s13, s12, 0x210000
	s_mul_hi_i32 s9, s12, 0x210000
	s_add_u32 s10, s54, s13
	s_addc_u32 s11, s55, s9
	s_add_u32 s10, s10, s8
	s_addc_u32 s11, s11, 0
	s_add_u32 s13, s56, s13
	s_addc_u32 s9, s57, s9
	s_add_u32 s8, s13, s8
	s_addc_u32 s9, s9, 0
	s_mul_hi_i32 s13, s12, 0x10800
	s_mul_i32 s12, s12, 0x10800
	s_add_u32 s12, s42, s12
	s_addc_u32 s13, s43, s13
	s_mov_b64 s[48:49], 0
	s_mov_b64 s[46:47], s[28:29]
	s_mov_b32 s28, s53
